# ffn_in: workgroups 172..255 (5 tiles instead of 6) start 12 us late so that their epilogues fall into the others' K-loops
# speedup vs baseline: 1.1914x; 1.0011x over previous
; __device__ __forceinline__ int lane_id_v() { int l; asm volatile("v_mbcnt_lo_u32_b32 %0, -1, 0\n\tv_mbcnt_hi_u32_b32 %0, -1, %0" : "=v"(l)); return l; }
; __global__ void __launch_bounds__(512, 2) mega(Args a_unused) {
;     ...
;     for (int ph = ph_lo; ph < ph_hi; ++ph) {
;         const int kk9 = (ph - 2) % 9;
;         const int cls = ph == 0 ? 0 : ph == 1 ? 1 : ph == NPHASE - 1 ? 10 : (kk9 == 0 || kk9 == 6) ? 2 : kk9 == 1 ? 3 : kk9 == 2 ? 4 : kk9 == 3 ? 5 : kk9 == 4 ? 6 : kk9 == 5 ? 7 : kk9 == 7 ? 8 : 9;
;     ...
;             else if (k == 7) { if (GM & 16) {
;                 pg8::Gemm g{H, (const bf16_t*)(ws + WS_WFI) + (size_t)l * 2 * DFF * 1024, M, 2 * DFF, 1024}; pg8::StaticOrder S; S.init(M, 2 * DFF, G, c);
;                 pg8::EpiFfn E{(bf16_t*)(ws + WS_GT)};
;                 pg8::gemm_phase<pg8::EpiFfn, pg8::StaticOrder, true, true>(lds, g, S, E, wave_s * 64 + lane_id_v()); }
.LBB0_192:
	v_writelane_b32 v254, s86, 27
	s_add_i32 s0, s86, -2
	s_mul_hi_i32 s1, s0, 0x38e38e39
	s_lshr_b32 s2, s1, 31
	s_ashr_i32 s1, s1, 1
	s_add_i32 s2, s1, s2
	s_mul_i32 s1, s2, 9
	v_writelane_b32 v254, s87, 28
	s_sub_i32 s86, s0, s1
	s_mul_i32 s0, s2, 0x1800
	s_ashr_i32 s1, s0, 31
	v_writelane_b32 v254, s0, 29
	s_ashr_i32 s3, s2, 31
	s_mov_b64 s[4:5], 0
	v_writelane_b32 v254, s1, 30
	v_writelane_b32 v254, s2, 31
	s_lshl_b32 s0, s2, 10
	s_ashr_i32 s1, s0, 31
	v_writelane_b32 v254, s3, 32
	v_writelane_b32 v254, s0, 33
	s_add_u32 s88, s26, 0x8f00000
	s_addc_u32 s89, s27, 0
	v_writelane_b32 v254, s1, 34
	v_writelane_b32 v254, s4, 35
	s_mov_b64 s[2:3], -1
	s_mov_b64 s[0:1], 0
	s_cmp_lt_i32 s86, 4
	v_writelane_b32 v254, s5, 36
	s_cbranch_scc1 .LBB0_448
	s_cmp_gt_i32 s86, 5
	s_cbranch_scc0 .LBB0_219
	s_cmp_gt_i32 s86, 6
	s_cbranch_scc0 .LBB0_220
	s_cmp_eq_u32 s86, 7
	s_cbranch_scc0 .LBB0_224
	v_mbcnt_lo_u32_b32 v0, -1, 0
	v_mbcnt_hi_u32_b32 v0, -1, v0
	s_cmpk_gt_i32 s38, 0x5ab
	v_add_u32_e32 v14, s90, v0
	s_nop 0
	v_readfirstlane_b32 s6, v14
	s_cbranch_scc1 .LBB0_223
	s_cmpk_lt_i32 s38, 0xac
	s_cbranch_scc1 .Lds_nosleep
	s_sleep 127
	s_sleep 127
	s_sleep 127
.Lds_nosleep:
	s_ashr_i32 s30, s38, 31
	s_lshr_b32 s2, s30, 29
	s_add_i32 s5, s38, s2
	s_and_b32 s2, s5, -8
	s_sub_i32 s7, s38, s2
	s_cmp_gt_i32 s7, 3
	s_mov_b64 s[2:3], -1
	s_cbranch_scc0 .LBB0_199
	s_mul_i32 s2, s7, 0xb5
	s_add_i32 s4, s2, 4
	s_mov_b64 s[2:3], 0
